# cooperative-groups grid.sync after the weight-conversion phase replaced by the kernel's own XCD-hierarchical grid barrier
# speedup vs baseline: 1.0077x; 1.0077x over previous
; #define LAS3 __attribute__((address_space(3)))
; DI unsigned xb_ld(unsigned* p) { return __hip_atomic_load(p, __ATOMIC_RELAXED, __HIP_MEMORY_SCOPE_AGENT); }
; DI void xcd_barrier_complete(unsigned* bar, unsigned x, unsigned& nloc, unsigned& nx) {
;   const unsigned G = gridDim.x * gridDim.y * gridDim.z;
;   unsigned sum, cnt, mine, sp = 0u;
;   for (;;) {
;     sum = 0u; cnt = 0u; mine = 0u;
; #pragma unroll
;     for (unsigned j = 0; j < 16; ++j) { const unsigned c = xb_ld(&bar[XB_XCNT(j)]); sum += c; cnt += (c > 0u) ? 1u : 0u; mine = (j == x) ? c : mine; }
;     if (sum == G) break;
; DI void xcd_barrier(unsigned* bar, const unsigned x, volatile LAS3 unsigned* st) {
;   asm volatile("s_waitcnt vmcnt(0)" ::: "memory");
;   __syncthreads();
;   if (threadIdx.x == 0) {
;     __builtin_amdgcn_s_waitcnt(0);
;     unsigned nloc = st[0], nx = st[1];
;     if (nloc == 0u) { xcd_barrier_complete(bar, x, nloc, nx); st[0] = nloc; st[1] = nx; }
.LBB0_60:
	s_or_b64 exec, exec, s[4:5]
	s_load_dwordx2 s[6:7], s[0:1], 0xb0
	s_waitcnt lgkmcnt(0)
	s_load_dwordx2 s[4:5], s[0:1], 0xb8
	s_getreg_b32 s8, hwreg(HW_REG_XCC_ID, 0, 4)
	s_waitcnt vmcnt(0)
	s_waitcnt vmcnt(0) lgkmcnt(0)
	s_barrier
	s_and_saveexec_b64 s[4:5], s[10:11]
	s_cbranch_execz .Lmy_gb0_442
	s_add_i32 s9, 0, 0x20000
	v_mov_b32_e32 v0, s9
	s_waitcnt vmcnt(0) expcnt(0) lgkmcnt(0)
	ds_read_b32 v2, v0
	s_add_i32 s9, 0, 0x20004
	v_mov_b32_e32 v0, s9
	ds_read_b32 v0, v0
	s_and_b32 s54, s8, 15
	s_waitcnt lgkmcnt(1)
	v_cmp_ne_u32_e32 vcc, 0, v2
	s_cbranch_vccnz .Lmy_gb0_406
	s_add_u32 s8, s6, 0x2f80200
	s_addc_u32 s9, s7, 0
	s_add_u32 s14, s6, 0x2f80400
	s_addc_u32 s15, s7, 0
	s_add_u32 s16, s6, 0x2f80500
	s_addc_u32 s17, s7, 0
	s_add_u32 s18, s6, 0x2f80600
	s_addc_u32 s19, s7, 0
	s_add_u32 s20, s6, 0x2f80700
	s_addc_u32 s21, s7, 0
	s_add_u32 s22, s6, 0x2f80800
	s_addc_u32 s23, s7, 0
	s_add_u32 s24, s6, 0x2f80900
	s_addc_u32 s25, s7, 0
	s_add_u32 s26, s6, 0x2f80a00
	s_addc_u32 s27, s7, 0
	s_add_u32 s28, s6, 0x2f80b00
	s_addc_u32 s29, s7, 0
	s_add_u32 s30, s6, 0x2f80c00
	s_addc_u32 s31, s7, 0
	s_add_u32 s34, s6, 0x2f80d00
	s_addc_u32 s35, s7, 0
	s_add_u32 s36, s6, 0x2f80e00
	s_addc_u32 s37, s7, 0
	s_add_u32 s38, s6, 0x2f80f00
	s_addc_u32 s39, s7, 0
	s_add_u32 s40, s6, 0x2f81000
	s_addc_u32 s41, s7, 0
	s_add_u32 s42, s6, 0x2f81100
	s_addc_u32 s43, s7, 0
	s_add_u32 s44, s6, 0x2f81200
	s_addc_u32 s45, s7, 0
	s_mul_i32 s55, s13, s33
	s_add_u32 s46, s6, 0x2f81300
	s_mul_i32 s55, s55, s12
	s_addc_u32 s47, s7, 0
	s_mov_b32 s57, 1
	v_mov_b32_e32 v16, 0
	s_branch .Lmy_gb0_394

;   DI bool next(int i, Unit& u) const {
;     const long Lx = (long)i * G + c; if (__builtin_amdgcn_readfirstlane((int)(Lx >= nwg))) return false;
;     int wgid = (int)Lx; { const int q = nwg / NXCD, r = nwg % NXCD, xcd = wgid % NXCD, off = wgid / NXCD; wgid = (xcd < r ? xcd * (q + 1) : r * (q + 1) + (xcd - r) * q) + off; }
; DI void xcd_barrier(unsigned* bar, const unsigned x, volatile LAS3 unsigned* st) {
;     ...
;     }
;   }
;   __syncthreads();
.Lmy_gb0_442:
	s_or_b64 exec, exec, s[4:5]
	s_waitcnt lgkmcnt(0)
	s_barrier
	v_cvt_f32_u32_e32 v0, s12
	s_load_dwordx2 s[4:5], s[0:1], 0x0
	v_rcp_iflag_f32_e32 v0, v0
	s_waitcnt lgkmcnt(0)
	s_waitcnt lgkmcnt(0)
	s_load_dwordx2 s[4:5], s[0:1], 0x18
	v_mul_f32_e32 v0, 0x4f7ffffe, v0
	v_cvt_u32_f32_e32 v0, v0
	s_waitcnt lgkmcnt(0)
	s_load_dwordx2 s[14:15], s[0:1], 0xb0
	s_load_dwordx2 s[4:5], s[0:1], 0xb8
	s_waitcnt lgkmcnt(0)
	s_sub_i32 s5, 0, s12
	v_readfirstlane_b32 s56, v0
	s_mul_i32 s5, s5, s56
	s_mul_hi_u32 s5, s56, s5
	s_mov_b32 s4, s2
	s_add_i32 s56, s56, s5
	s_mul_hi_u32 s5, s4, s56
	s_mul_i32 s5, s5, s12
	s_sub_i32 s4, s4, s5
	s_sub_i32 s5, s4, s12
	s_cmp_ge_u32 s4, s12
	s_cselect_b32 s4, s5, s4
	s_sub_i32 s5, s4, s12
	s_cmp_ge_u32 s4, s12
	s_cselect_b32 s57, s5, s4
	s_cmpk_gt_i32 s57, 0xd91
	s_cselect_b64 s[4:5], -1, 0
	v_cndmask_b32_e64 v0, 0, 1, s[4:5]
	v_mbcnt_lo_u32_b32 v8, -1, 0
	v_mbcnt_hi_u32_b32 v8, -1, v8
	v_lshl_or_b32 v8, s3, 6, v8
	s_mov_b64 s[6:7], -1
	v_readfirstlane_b32 s4, v0
	s_bitcmp1_b32 s4, 0
	s_cselect_b64 s[4:5], -1, 0
	v_readfirstlane_b32 s58, v8
	s_and_b64 vcc, exec, s[4:5]
	s_cbranch_vccnz .LBB0_76
	s_ashr_i32 s8, s57, 31
	s_lshr_b32 s8, s8, 29
	s_add_i32 s16, s57, s8
	s_and_b32 s8, s16, -8
	s_sub_i32 s8, s57, s8
	s_cmp_gt_i32 s8, 1
	s_cbranch_scc0 .LBB0_73
	s_mul_i32 s6, s8, 0x1b2
	s_add_i32 s9, s6, 2
	s_mov_b64 s[6:7], 0
